# o30 + upper half (kb>=16) of the FFN2 gate/up fold conversion done in WIN's idle round by the hand-written wave-queue converter before the compiled filler loop
# baseline (speedup 1.0000x reference)
.LBB0_1169:
	s_waitcnt vmcnt(0)
	v_readlane_b32 s80, v254, 8
	v_readlane_b32 s81, v254, 9
	v_readlane_b32 s82, v254, 10
	v_readlane_b32 s83, v254, 11
	v_readlane_b32 s84, v254, 12
	v_readlane_b32 s85, v254, 13
	v_readlane_b32 s86, v254, 14
	v_readlane_b32 s87, v254, 15
	s_barrier
	v_readlane_b32 s101, v253, 0
	s_nop 3
	s_cmpk_lt_u32 s101, 0x61
	s_cbranch_scc1 .LBB0_1170
	s_mov_b64 exec, -1
	v_lshlrev_b32_e32 v2, 4, v0
	v_add_u32_e32 v3, 0x10000, v2
	ds_write_b128 v2, v[66:69] offset:0
	ds_write_b128 v2, v[70:73] offset:8192
	ds_write_b128 v2, v[74:77] offset:16384
	ds_write_b128 v2, v[78:81] offset:24576
	ds_write_b128 v2, v[82:85] offset:32768
	ds_write_b128 v2, v[86:89] offset:40960
	ds_write_b128 v2, v[90:93] offset:49152
	ds_write_b128 v2, v[94:97] offset:57344
	ds_write_b128 v3, v[98:101] offset:0
	ds_write_b128 v3, v[102:105] offset:8192
	ds_write_b128 v3, v[106:109] offset:16384
	ds_write_b128 v3, v[110:113] offset:24576
	ds_write_b128 v3, v[114:117] offset:32768
	ds_write_b128 v3, v[118:121] offset:40960
	ds_write_b128 v3, v[122:125] offset:49152
	ds_write_b128 v3, v[126:129] offset:57344
	v_readlane_b32 s0, v253, 21
	v_readlane_b32 s1, v253, 22
	s_nop 3
	s_sub_u32 s0, s0, 0xe0
	s_subb_u32 s1, s1, 0
	s_load_dwordx8 s[56:63], s[0:1], 0x98
	s_add_u32 s6, s86, 0xca00
	s_addc_u32 s7, s87, 0
	s_add_u32 s64, s86, 0x54000
	s_addc_u32 s65, s87, 0
	s_add_u32 s66, s86, 0x60000
	s_addc_u32 s67, s87, 0
	s_add_u32 s68, s86, 0x8c60200
	s_addc_u32 s69, s87, 0
	v_and_b32_e32 v6, 15, v0
	v_and_b32_e32 v7, 48, v0
	s_waitcnt lgkmcnt(0)
	v_mul_u32_u24_e32 v124, 0x5800, v7
	v_lshl_add_u32 v124, v6, 4, v124
	v_lshlrev_b32_e32 v125, 2, v6
	v_lshlrev_b32_e32 v126, 2, v7
	v_and_b32_e32 v19, 63, v0
	v_xor_b32_e32 v48, 16, v19
	v_lshlrev_b32_e32 v48, 2, v48
	v_xor_b32_e32 v1, 32, v19
	v_lshlrev_b32_e32 v1, 2, v1
	v_cmp_gt_u32_e64 s[36:37], 16, v19
	v_mov_b32_e32 v16, 0
	v_mov_b32_e32 v17, 1
	s_mov_b64 exec, 1
	global_atomic_add v18, v16, v17, s[6:7] sc0
	s_mov_b64 exec, -1
	s_waitcnt vmcnt(0)
.Lw2tw_loop:
	v_readfirstlane_b32 s98, v18
	s_nop 3
	s_cmpk_ge_u32 s98, 0x580
	s_cbranch_scc1 .Lw2tw_rest
	s_lshl_b32 s99, s98, 1
	s_add_u32 s99, s99, 0xb00
	s_mul_i32 s100, s99, 0xba2f
	s_lshr_b32 s100, s100, 23
	s_mul_i32 s101, s100, 0xb0
	s_sub_u32 s101, s99, s101
	s_and_b32 s70, s101, 2
	s_cmp_eq_u32 s70, 0
	s_cselect_b32 s72, s60, s62
	s_cselect_b32 s73, s61, s63
	s_lshr_b32 s70, s101, 2
	s_lshl_b32 s70, s70, 9
	s_mul_i32 s71, s100, 0x160000
	s_add_u32 s70, s70, s71
	s_add_u32 s0, s72, s70
	s_addc_u32 s1, s73, 0
	s_lshl_b32 s70, s101, 18
	s_lshl_b32 s71, s100, 7
	s_add_u32 s70, s70, s71
	s_add_u32 s2, s68, s70
	s_addc_u32 s3, s69, 0
	s_add_u32 s4, s2, 0x40000
	s_addc_u32 s5, s3, 0
	s_lshl_b32 s70, s101, 8
	s_add_u32 s72, s64, s70
	s_addc_u32 s73, s65, 0
	s_add_u32 s74, s66, s70
	s_addc_u32 s75, s67, 0
	s_add_u32 s76, s72, 0x100
	s_addc_u32 s77, s73, 0
	s_add_u32 s78, s74, 0x100
	s_addc_u32 s79, s75, 0
	s_lshl_b32 s70, s100, 8
	s_add_u32 s32, s56, s70
	s_addc_u32 s33, s57, 0
	s_add_u32 s34, s58, s70
	s_addc_u32 s35, s59, 0
	global_load_dwordx4 v[66:69], v126, s[32:33] offset:0
	global_load_dwordx4 v[82:85], v126, s[34:35] offset:0
	global_load_dwordx4 v[70:73], v126, s[32:33] offset:16
	global_load_dwordx4 v[86:89], v126, s[34:35] offset:16
	global_load_dwordx4 v[74:77], v126, s[32:33] offset:32
	global_load_dwordx4 v[90:93], v126, s[34:35] offset:32
	global_load_dwordx4 v[78:81], v126, s[32:33] offset:48
	global_load_dwordx4 v[94:97], v126, s[34:35] offset:48
	global_load_dwordx4 v[154:157], v124, s[0:1] nt
	global_load_dwordx4 v[204:207], v124, s[0:1] offset:256 nt
	s_add_u32 s0, s0, 0x5800
	s_addc_u32 s1, s1, 0
	global_load_dwordx4 v[158:161], v124, s[0:1] nt
	global_load_dwordx4 v[208:211], v124, s[0:1] offset:256 nt
	s_add_u32 s0, s0, 0x5800
	s_addc_u32 s1, s1, 0
	global_load_dwordx4 v[162:165], v124, s[0:1] nt
	global_load_dwordx4 v[212:215], v124, s[0:1] offset:256 nt
	s_add_u32 s0, s0, 0x5800
	s_addc_u32 s1, s1, 0
	global_load_dwordx4 v[166:169], v124, s[0:1] nt
	global_load_dwordx4 v[216:219], v124, s[0:1] offset:256 nt
	s_add_u32 s0, s0, 0x5800
	s_addc_u32 s1, s1, 0
	global_load_dwordx4 v[170:173], v124, s[0:1] nt
	global_load_dwordx4 v[220:223], v124, s[0:1] offset:256 nt
	s_add_u32 s0, s0, 0x5800
	s_addc_u32 s1, s1, 0
	global_load_dwordx4 v[174:177], v124, s[0:1] nt
	global_load_dwordx4 v[224:227], v124, s[0:1] offset:256 nt
	s_add_u32 s0, s0, 0x5800
	s_addc_u32 s1, s1, 0
	global_load_dwordx4 v[178:181], v124, s[0:1] nt
	global_load_dwordx4 v[228:231], v124, s[0:1] offset:256 nt
	s_add_u32 s0, s0, 0x5800
	s_addc_u32 s1, s1, 0
	global_load_dwordx4 v[182:185], v124, s[0:1] nt
	global_load_dwordx4 v[232:235], v124, s[0:1] offset:256 nt
	s_add_u32 s0, s0, 0x5800
	s_addc_u32 s1, s1, 0
	global_load_dwordx4 v[186:189], v124, s[0:1] nt
	global_load_dwordx4 v[236:239], v124, s[0:1] offset:256 nt
	s_add_u32 s0, s0, 0x5800
	s_addc_u32 s1, s1, 0
	global_load_dwordx4 v[190:193], v124, s[0:1] nt
	global_load_dwordx4 v[240:243], v124, s[0:1] offset:256 nt
	s_add_u32 s0, s0, 0x5800
	s_addc_u32 s1, s1, 0
	global_load_dwordx4 v[194:197], v124, s[0:1] nt
	global_load_dwordx4 v[244:247], v124, s[0:1] offset:256 nt
	s_add_u32 s0, s0, 0x5800
	s_addc_u32 s1, s1, 0
	global_load_dwordx4 v[198:201], v124, s[0:1] nt
	global_load_dwordx4 v[248:251], v124, s[0:1] offset:256 nt
	s_add_u32 s0, s0, 0x5800
	s_addc_u32 s1, s1, 0
	global_load_dwordx4 v[130:133], v124, s[0:1] nt
	global_load_dwordx4 v[50:53], v124, s[0:1] offset:256 nt
	s_add_u32 s0, s0, 0x5800
	s_addc_u32 s1, s1, 0
	global_load_dwordx4 v[134:137], v124, s[0:1] nt
	global_load_dwordx4 v[54:57], v124, s[0:1] offset:256 nt
	s_add_u32 s0, s0, 0x5800
	s_addc_u32 s1, s1, 0
	global_load_dwordx4 v[138:141], v124, s[0:1] nt
	global_load_dwordx4 v[58:61], v124, s[0:1] offset:256 nt
	s_add_u32 s0, s0, 0x5800
	s_addc_u32 s1, s1, 0
	global_load_dwordx4 v[142:145], v124, s[0:1] nt
	global_load_dwordx4 v[62:65], v124, s[0:1] offset:256 nt
	s_mov_b64 exec, 1
	global_atomic_add v18, v16, v17, s[6:7] sc0
	s_mov_b64 exec, -1
	s_waitcnt vmcnt(1)
	v_mul_f32_e32 v98, v154, v82
	v_mul_f32_e32 v99, v155, v82
	v_mul_f32_e32 v100, v156, v82
	v_mul_f32_e32 v101, v157, v82
	v_mul_f32_e32 v154, v154, v66
	v_mul_f32_e32 v155, v155, v66
	v_mul_f32_e32 v156, v156, v66
	v_mul_f32_e32 v157, v157, v66
	v_fmac_f32_e32 v98, v158, v83
	v_fmac_f32_e32 v99, v159, v83
	v_fmac_f32_e32 v100, v160, v83
	v_fmac_f32_e32 v101, v161, v83
	v_mul_f32_e32 v158, v158, v67
	v_mul_f32_e32 v159, v159, v67
	v_mul_f32_e32 v160, v160, v67
	v_mul_f32_e32 v161, v161, v67
	v_fmac_f32_e32 v98, v162, v84
	v_fmac_f32_e32 v99, v163, v84
	v_fmac_f32_e32 v100, v164, v84
	v_fmac_f32_e32 v101, v165, v84
	v_mul_f32_e32 v162, v162, v68
	v_mul_f32_e32 v163, v163, v68
	v_mul_f32_e32 v164, v164, v68
	v_mul_f32_e32 v165, v165, v68
	v_fmac_f32_e32 v98, v166, v85
	v_fmac_f32_e32 v99, v167, v85
	v_fmac_f32_e32 v100, v168, v85
	v_fmac_f32_e32 v101, v169, v85
	v_mul_f32_e32 v166, v166, v69
	v_mul_f32_e32 v167, v167, v69
	v_mul_f32_e32 v168, v168, v69
	v_mul_f32_e32 v169, v169, v69
	v_fmac_f32_e32 v98, v170, v86
	v_fmac_f32_e32 v99, v171, v86
	v_fmac_f32_e32 v100, v172, v86
	v_fmac_f32_e32 v101, v173, v86
	v_mul_f32_e32 v170, v170, v70
	v_mul_f32_e32 v171, v171, v70
	v_mul_f32_e32 v172, v172, v70
	v_mul_f32_e32 v173, v173, v70
	v_fmac_f32_e32 v98, v174, v87
	v_fmac_f32_e32 v99, v175, v87
	v_fmac_f32_e32 v100, v176, v87
	v_fmac_f32_e32 v101, v177, v87
	v_mul_f32_e32 v174, v174, v71
	v_mul_f32_e32 v175, v175, v71
	v_mul_f32_e32 v176, v176, v71
	v_mul_f32_e32 v177, v177, v71
	v_fmac_f32_e32 v98, v178, v88
	v_fmac_f32_e32 v99, v179, v88
	v_fmac_f32_e32 v100, v180, v88
	v_fmac_f32_e32 v101, v181, v88
	v_mul_f32_e32 v178, v178, v72
	v_mul_f32_e32 v179, v179, v72
	v_mul_f32_e32 v180, v180, v72
	v_mul_f32_e32 v181, v181, v72
	v_fmac_f32_e32 v98, v182, v89
	v_fmac_f32_e32 v99, v183, v89
	v_fmac_f32_e32 v100, v184, v89
	v_fmac_f32_e32 v101, v185, v89
	v_mul_f32_e32 v182, v182, v73
	v_mul_f32_e32 v183, v183, v73
	v_mul_f32_e32 v184, v184, v73
	v_mul_f32_e32 v185, v185, v73
	v_fmac_f32_e32 v98, v186, v90
	v_fmac_f32_e32 v99, v187, v90
	v_fmac_f32_e32 v100, v188, v90
	v_fmac_f32_e32 v101, v189, v90
	v_mul_f32_e32 v186, v186, v74
	v_mul_f32_e32 v187, v187, v74
	v_mul_f32_e32 v188, v188, v74
	v_mul_f32_e32 v189, v189, v74
	v_fmac_f32_e32 v98, v190, v91
	v_fmac_f32_e32 v99, v191, v91
	v_fmac_f32_e32 v100, v192, v91
	v_fmac_f32_e32 v101, v193, v91
	v_mul_f32_e32 v190, v190, v75
	v_mul_f32_e32 v191, v191, v75
	v_mul_f32_e32 v192, v192, v75
	v_mul_f32_e32 v193, v193, v75
	v_fmac_f32_e32 v98, v194, v92
	v_fmac_f32_e32 v99, v195, v92
	v_fmac_f32_e32 v100, v196, v92
	v_fmac_f32_e32 v101, v197, v92
	v_mul_f32_e32 v194, v194, v76
	v_mul_f32_e32 v195, v195, v76
	v_mul_f32_e32 v196, v196, v76
	v_mul_f32_e32 v197, v197, v76
	v_fmac_f32_e32 v98, v198, v93
	v_fmac_f32_e32 v99, v199, v93
	v_fmac_f32_e32 v100, v200, v93
	v_fmac_f32_e32 v101, v201, v93
	v_mul_f32_e32 v198, v198, v77
	v_mul_f32_e32 v199, v199, v77
	v_mul_f32_e32 v200, v200, v77
	v_mul_f32_e32 v201, v201, v77
	v_fmac_f32_e32 v98, v130, v94
	v_fmac_f32_e32 v99, v131, v94
	v_fmac_f32_e32 v100, v132, v94
	v_fmac_f32_e32 v101, v133, v94
	v_mul_f32_e32 v130, v130, v78
	v_mul_f32_e32 v131, v131, v78
	v_mul_f32_e32 v132, v132, v78
	v_mul_f32_e32 v133, v133, v78
	v_fmac_f32_e32 v98, v134, v95
	v_fmac_f32_e32 v99, v135, v95
	v_fmac_f32_e32 v100, v136, v95
	v_fmac_f32_e32 v101, v137, v95
	v_mul_f32_e32 v134, v134, v79
	v_mul_f32_e32 v135, v135, v79
	v_mul_f32_e32 v136, v136, v79
	v_mul_f32_e32 v137, v137, v79
	v_fmac_f32_e32 v98, v138, v96
	v_fmac_f32_e32 v99, v139, v96
	v_fmac_f32_e32 v100, v140, v96
	v_fmac_f32_e32 v101, v141, v96
	v_mul_f32_e32 v138, v138, v80
	v_mul_f32_e32 v139, v139, v80
	v_mul_f32_e32 v140, v140, v80
	v_mul_f32_e32 v141, v141, v80
	v_fmac_f32_e32 v98, v142, v97
	v_fmac_f32_e32 v99, v143, v97
	v_fmac_f32_e32 v100, v144, v97
	v_fmac_f32_e32 v101, v145, v97
	v_mul_f32_e32 v142, v142, v81
	v_mul_f32_e32 v143, v143, v81
	v_mul_f32_e32 v144, v144, v81
	v_mul_f32_e32 v145, v145, v81
	v_lshlrev_b32_e32 v2, 2, v125
	v_lshlrev_b32_e32 v3, 12, v125
	v_lshl_add_u32 v3, v7, 1, v3
	ds_bpermute_b32 v106, v48, v98
	ds_bpermute_b32 v107, v48, v99
	ds_bpermute_b32 v108, v48, v100
	ds_bpermute_b32 v109, v48, v101
	s_waitcnt lgkmcnt(0)
	v_add_f32_e32 v98, v98, v106
	v_add_f32_e32 v99, v99, v107
	v_add_f32_e32 v100, v100, v108
	v_add_f32_e32 v101, v101, v109
	ds_bpermute_b32 v106, v1, v98
	ds_bpermute_b32 v107, v1, v99
	ds_bpermute_b32 v108, v1, v100
	ds_bpermute_b32 v109, v1, v101
	s_waitcnt lgkmcnt(0)
	v_add_f32_e32 v98, v98, v106
	v_add_f32_e32 v99, v99, v107
	v_add_f32_e32 v100, v100, v108
	v_add_f32_e32 v101, v101, v109
	s_mov_b64 exec, s[36:37]
	global_atomic_add_f32 v2, v98, s[74:75] offset:0
	global_atomic_add_f32 v2, v99, s[74:75] offset:4
	global_atomic_add_f32 v2, v100, s[74:75] offset:8
	global_atomic_add_f32 v2, v101, s[74:75] offset:12
	s_mov_b64 exec, -1
	v_cvt_pk_bf16_f32 v20, v154, v158
	v_cvt_pk_bf16_f32 v21, v162, v166
	v_cvt_pk_bf16_f32 v22, v170, v174
	v_cvt_pk_bf16_f32 v23, v178, v182
	global_store_dwordx4 v3, v[20:23], s[2:3]
	v_cvt_pk_bf16_f32 v24, v186, v190
	v_cvt_pk_bf16_f32 v25, v194, v198
	v_cvt_pk_bf16_f32 v26, v130, v134
	v_cvt_pk_bf16_f32 v27, v138, v142
	global_store_dwordx4 v3, v[24:27], s[2:3] offset:16
	v_lshlrev_b32_e32 v19, 16, v20
	v_and_b32_e32 v114, 0xffff0000, v20
	v_add_f32_e32 v114, v19, v114
	v_lshlrev_b32_e32 v19, 16, v21
	v_and_b32_e32 v115, 0xffff0000, v21
	v_add_f32_e32 v115, v19, v115
	v_lshlrev_b32_e32 v19, 16, v22
	v_and_b32_e32 v116, 0xffff0000, v22
	v_add_f32_e32 v116, v19, v116
	v_lshlrev_b32_e32 v19, 16, v23
	v_and_b32_e32 v117, 0xffff0000, v23
	v_add_f32_e32 v117, v19, v117
	v_lshlrev_b32_e32 v19, 16, v24
	v_and_b32_e32 v118, 0xffff0000, v24
	v_add_f32_e32 v118, v19, v118
	v_lshlrev_b32_e32 v19, 16, v25
	v_and_b32_e32 v119, 0xffff0000, v25
	v_add_f32_e32 v119, v19, v119
	v_lshlrev_b32_e32 v19, 16, v26
	v_and_b32_e32 v120, 0xffff0000, v26
	v_add_f32_e32 v120, v19, v120
	v_lshlrev_b32_e32 v19, 16, v27
	v_and_b32_e32 v121, 0xffff0000, v27
	v_add_f32_e32 v121, v19, v121
	v_add_f32_e32 v114, v114, v115
	v_add_f32_e32 v116, v116, v117
	v_add_f32_e32 v118, v118, v119
	v_add_f32_e32 v120, v120, v121
	v_add_f32_e32 v114, v114, v116
	v_add_f32_e32 v118, v118, v120
	v_add_f32_e32 v110, v114, v118
	s_add_u32 s2, s2, 0x1000
	s_addc_u32 s3, s3, 0
	v_cvt_pk_bf16_f32 v28, v155, v159
	v_cvt_pk_bf16_f32 v29, v163, v167
	v_cvt_pk_bf16_f32 v30, v171, v175
	v_cvt_pk_bf16_f32 v31, v179, v183
	global_store_dwordx4 v3, v[28:31], s[2:3]
	v_cvt_pk_bf16_f32 v32, v187, v191
	v_cvt_pk_bf16_f32 v33, v195, v199
	v_cvt_pk_bf16_f32 v34, v131, v135
	v_cvt_pk_bf16_f32 v35, v139, v143
	global_store_dwordx4 v3, v[32:35], s[2:3] offset:16
	v_lshlrev_b32_e32 v19, 16, v28
	v_and_b32_e32 v114, 0xffff0000, v28
	v_add_f32_e32 v114, v19, v114
	v_lshlrev_b32_e32 v19, 16, v29
	v_and_b32_e32 v115, 0xffff0000, v29
	v_add_f32_e32 v115, v19, v115
	v_lshlrev_b32_e32 v19, 16, v30
	v_and_b32_e32 v116, 0xffff0000, v30
	v_add_f32_e32 v116, v19, v116
	v_lshlrev_b32_e32 v19, 16, v31
	v_and_b32_e32 v117, 0xffff0000, v31
	v_add_f32_e32 v117, v19, v117
	v_lshlrev_b32_e32 v19, 16, v32
	v_and_b32_e32 v118, 0xffff0000, v32
	v_add_f32_e32 v118, v19, v118
	v_lshlrev_b32_e32 v19, 16, v33
	v_and_b32_e32 v119, 0xffff0000, v33
	v_add_f32_e32 v119, v19, v119
	v_lshlrev_b32_e32 v19, 16, v34
	v_and_b32_e32 v120, 0xffff0000, v34
	v_add_f32_e32 v120, v19, v120
	v_lshlrev_b32_e32 v19, 16, v35
	v_and_b32_e32 v121, 0xffff0000, v35
	v_add_f32_e32 v121, v19, v121
	v_add_f32_e32 v114, v114, v115
	v_add_f32_e32 v116, v116, v117
	v_add_f32_e32 v118, v118, v119
	v_add_f32_e32 v120, v120, v121
	v_add_f32_e32 v114, v114, v116
	v_add_f32_e32 v118, v118, v120
	v_add_f32_e32 v111, v114, v118
	s_add_u32 s2, s2, 0x1000
	s_addc_u32 s3, s3, 0
	v_cvt_pk_bf16_f32 v36, v156, v160
	v_cvt_pk_bf16_f32 v37, v164, v168
	v_cvt_pk_bf16_f32 v38, v172, v176
	v_cvt_pk_bf16_f32 v39, v180, v184
	global_store_dwordx4 v3, v[36:39], s[2:3]
	v_cvt_pk_bf16_f32 v40, v188, v192
	v_cvt_pk_bf16_f32 v41, v196, v200
	v_cvt_pk_bf16_f32 v42, v132, v136
	v_cvt_pk_bf16_f32 v43, v140, v144
	global_store_dwordx4 v3, v[40:43], s[2:3] offset:16
	v_lshlrev_b32_e32 v19, 16, v36
	v_and_b32_e32 v114, 0xffff0000, v36
	v_add_f32_e32 v114, v19, v114
	v_lshlrev_b32_e32 v19, 16, v37
	v_and_b32_e32 v115, 0xffff0000, v37
	v_add_f32_e32 v115, v19, v115
	v_lshlrev_b32_e32 v19, 16, v38
	v_and_b32_e32 v116, 0xffff0000, v38
	v_add_f32_e32 v116, v19, v116
	v_lshlrev_b32_e32 v19, 16, v39
	v_and_b32_e32 v117, 0xffff0000, v39
	v_add_f32_e32 v117, v19, v117
	v_lshlrev_b32_e32 v19, 16, v40
	v_and_b32_e32 v118, 0xffff0000, v40
	v_add_f32_e32 v118, v19, v118
	v_lshlrev_b32_e32 v19, 16, v41
	v_and_b32_e32 v119, 0xffff0000, v41
	v_add_f32_e32 v119, v19, v119
	v_lshlrev_b32_e32 v19, 16, v42
	v_and_b32_e32 v120, 0xffff0000, v42
	v_add_f32_e32 v120, v19, v120
	v_lshlrev_b32_e32 v19, 16, v43
	v_and_b32_e32 v121, 0xffff0000, v43
	v_add_f32_e32 v121, v19, v121
	v_add_f32_e32 v114, v114, v115
	v_add_f32_e32 v116, v116, v117
	v_add_f32_e32 v118, v118, v119
	v_add_f32_e32 v120, v120, v121
	v_add_f32_e32 v114, v114, v116
	v_add_f32_e32 v118, v118, v120
	v_add_f32_e32 v112, v114, v118
	s_add_u32 s2, s2, 0x1000
	s_addc_u32 s3, s3, 0
	v_cvt_pk_bf16_f32 v20, v157, v161
	v_cvt_pk_bf16_f32 v21, v165, v169
	v_cvt_pk_bf16_f32 v22, v173, v177
	v_cvt_pk_bf16_f32 v23, v181, v185
	global_store_dwordx4 v3, v[20:23], s[2:3]
	v_cvt_pk_bf16_f32 v24, v189, v193
	v_cvt_pk_bf16_f32 v25, v197, v201
	v_cvt_pk_bf16_f32 v26, v133, v137
	v_cvt_pk_bf16_f32 v27, v141, v145
	global_store_dwordx4 v3, v[24:27], s[2:3] offset:16
	v_lshlrev_b32_e32 v19, 16, v20
	v_and_b32_e32 v114, 0xffff0000, v20
	v_add_f32_e32 v114, v19, v114
	v_lshlrev_b32_e32 v19, 16, v21
	v_and_b32_e32 v115, 0xffff0000, v21
	v_add_f32_e32 v115, v19, v115
	v_lshlrev_b32_e32 v19, 16, v22
	v_and_b32_e32 v116, 0xffff0000, v22
	v_add_f32_e32 v116, v19, v116
	v_lshlrev_b32_e32 v19, 16, v23
	v_and_b32_e32 v117, 0xffff0000, v23
	v_add_f32_e32 v117, v19, v117
	v_lshlrev_b32_e32 v19, 16, v24
	v_and_b32_e32 v118, 0xffff0000, v24
	v_add_f32_e32 v118, v19, v118
	v_lshlrev_b32_e32 v19, 16, v25
	v_and_b32_e32 v119, 0xffff0000, v25
	v_add_f32_e32 v119, v19, v119
	v_lshlrev_b32_e32 v19, 16, v26
	v_and_b32_e32 v120, 0xffff0000, v26
	v_add_f32_e32 v120, v19, v120
	v_lshlrev_b32_e32 v19, 16, v27
	v_and_b32_e32 v121, 0xffff0000, v27
	v_add_f32_e32 v121, v19, v121
	v_add_f32_e32 v114, v114, v115
	v_add_f32_e32 v116, v116, v117
	v_add_f32_e32 v118, v118, v119
	v_add_f32_e32 v120, v120, v121
	v_add_f32_e32 v114, v114, v116
	v_add_f32_e32 v118, v118, v120
	v_add_f32_e32 v113, v114, v118
	ds_bpermute_b32 v106, v48, v110
	ds_bpermute_b32 v107, v48, v111
	ds_bpermute_b32 v108, v48, v112
	ds_bpermute_b32 v109, v48, v113
	s_waitcnt lgkmcnt(0)
	v_add_f32_e32 v110, v110, v106
	v_add_f32_e32 v111, v111, v107
	v_add_f32_e32 v112, v112, v108
	v_add_f32_e32 v113, v113, v109
	ds_bpermute_b32 v106, v1, v110
	ds_bpermute_b32 v107, v1, v111
	ds_bpermute_b32 v108, v1, v112
	ds_bpermute_b32 v109, v1, v113
	s_waitcnt lgkmcnt(0)
	v_add_f32_e32 v110, v110, v106
	v_add_f32_e32 v111, v111, v107
	v_add_f32_e32 v112, v112, v108
	v_add_f32_e32 v113, v113, v109
	s_mov_b64 exec, s[36:37]
	global_atomic_add_f32 v2, v110, s[72:73] offset:0
	global_atomic_add_f32 v2, v111, s[72:73] offset:4
	global_atomic_add_f32 v2, v112, s[72:73] offset:8
	global_atomic_add_f32 v2, v113, s[72:73] offset:12
	s_mov_b64 exec, -1
	v_mul_f32_e32 v98, v204, v82
	v_mul_f32_e32 v99, v205, v82
	v_mul_f32_e32 v100, v206, v82
	v_mul_f32_e32 v101, v207, v82
	v_mul_f32_e32 v204, v204, v66
	v_mul_f32_e32 v205, v205, v66
	v_mul_f32_e32 v206, v206, v66
	v_mul_f32_e32 v207, v207, v66
	v_fmac_f32_e32 v98, v208, v83
	v_fmac_f32_e32 v99, v209, v83
	v_fmac_f32_e32 v100, v210, v83
	v_fmac_f32_e32 v101, v211, v83
	v_mul_f32_e32 v208, v208, v67
	v_mul_f32_e32 v209, v209, v67
	v_mul_f32_e32 v210, v210, v67
	v_mul_f32_e32 v211, v211, v67
	v_fmac_f32_e32 v98, v212, v84
	v_fmac_f32_e32 v99, v213, v84
	v_fmac_f32_e32 v100, v214, v84
	v_fmac_f32_e32 v101, v215, v84
	v_mul_f32_e32 v212, v212, v68
	v_mul_f32_e32 v213, v213, v68
	v_mul_f32_e32 v214, v214, v68
	v_mul_f32_e32 v215, v215, v68
	v_fmac_f32_e32 v98, v216, v85
	v_fmac_f32_e32 v99, v217, v85
	v_fmac_f32_e32 v100, v218, v85
	v_fmac_f32_e32 v101, v219, v85
	v_mul_f32_e32 v216, v216, v69
	v_mul_f32_e32 v217, v217, v69
	v_mul_f32_e32 v218, v218, v69
	v_mul_f32_e32 v219, v219, v69
	v_fmac_f32_e32 v98, v220, v86
	v_fmac_f32_e32 v99, v221, v86
	v_fmac_f32_e32 v100, v222, v86
	v_fmac_f32_e32 v101, v223, v86
	v_mul_f32_e32 v220, v220, v70
	v_mul_f32_e32 v221, v221, v70
	v_mul_f32_e32 v222, v222, v70
	v_mul_f32_e32 v223, v223, v70
	v_fmac_f32_e32 v98, v224, v87
	v_fmac_f32_e32 v99, v225, v87
	v_fmac_f32_e32 v100, v226, v87
	v_fmac_f32_e32 v101, v227, v87
	v_mul_f32_e32 v224, v224, v71
	v_mul_f32_e32 v225, v225, v71
	v_mul_f32_e32 v226, v226, v71
	v_mul_f32_e32 v227, v227, v71
	v_fmac_f32_e32 v98, v228, v88
	v_fmac_f32_e32 v99, v229, v88
	v_fmac_f32_e32 v100, v230, v88
	v_fmac_f32_e32 v101, v231, v88
	v_mul_f32_e32 v228, v228, v72
	v_mul_f32_e32 v229, v229, v72
	v_mul_f32_e32 v230, v230, v72
	v_mul_f32_e32 v231, v231, v72
	v_fmac_f32_e32 v98, v232, v89
	v_fmac_f32_e32 v99, v233, v89
	v_fmac_f32_e32 v100, v234, v89
	v_fmac_f32_e32 v101, v235, v89
	v_mul_f32_e32 v232, v232, v73
	v_mul_f32_e32 v233, v233, v73
	v_mul_f32_e32 v234, v234, v73
	v_mul_f32_e32 v235, v235, v73
	v_fmac_f32_e32 v98, v236, v90
	v_fmac_f32_e32 v99, v237, v90
	v_fmac_f32_e32 v100, v238, v90
	v_fmac_f32_e32 v101, v239, v90
	v_mul_f32_e32 v236, v236, v74
	v_mul_f32_e32 v237, v237, v74
	v_mul_f32_e32 v238, v238, v74
	v_mul_f32_e32 v239, v239, v74
	v_fmac_f32_e32 v98, v240, v91
	v_fmac_f32_e32 v99, v241, v91
	v_fmac_f32_e32 v100, v242, v91
	v_fmac_f32_e32 v101, v243, v91
	v_mul_f32_e32 v240, v240, v75
	v_mul_f32_e32 v241, v241, v75
	v_mul_f32_e32 v242, v242, v75
	v_mul_f32_e32 v243, v243, v75
	v_fmac_f32_e32 v98, v244, v92
	v_fmac_f32_e32 v99, v245, v92
	v_fmac_f32_e32 v100, v246, v92
	v_fmac_f32_e32 v101, v247, v92
	v_mul_f32_e32 v244, v244, v76
	v_mul_f32_e32 v245, v245, v76
	v_mul_f32_e32 v246, v246, v76
	v_mul_f32_e32 v247, v247, v76
	v_fmac_f32_e32 v98, v248, v93
	v_fmac_f32_e32 v99, v249, v93
	v_fmac_f32_e32 v100, v250, v93
	v_fmac_f32_e32 v101, v251, v93
	v_mul_f32_e32 v248, v248, v77
	v_mul_f32_e32 v249, v249, v77
	v_mul_f32_e32 v250, v250, v77
	v_mul_f32_e32 v251, v251, v77
	v_fmac_f32_e32 v98, v50, v94
	v_fmac_f32_e32 v99, v51, v94
	v_fmac_f32_e32 v100, v52, v94
	v_fmac_f32_e32 v101, v53, v94
	v_mul_f32_e32 v50, v50, v78
	v_mul_f32_e32 v51, v51, v78
	v_mul_f32_e32 v52, v52, v78
	v_mul_f32_e32 v53, v53, v78
	v_fmac_f32_e32 v98, v54, v95
	v_fmac_f32_e32 v99, v55, v95
	v_fmac_f32_e32 v100, v56, v95
	v_fmac_f32_e32 v101, v57, v95
	v_mul_f32_e32 v54, v54, v79
	v_mul_f32_e32 v55, v55, v79
	v_mul_f32_e32 v56, v56, v79
	v_mul_f32_e32 v57, v57, v79
	v_fmac_f32_e32 v98, v58, v96
	v_fmac_f32_e32 v99, v59, v96
	v_fmac_f32_e32 v100, v60, v96
	v_fmac_f32_e32 v101, v61, v96
	v_mul_f32_e32 v58, v58, v80
	v_mul_f32_e32 v59, v59, v80
	v_mul_f32_e32 v60, v60, v80
	v_mul_f32_e32 v61, v61, v80
	v_fmac_f32_e32 v98, v62, v97
	v_fmac_f32_e32 v99, v63, v97
	v_fmac_f32_e32 v100, v64, v97
	v_fmac_f32_e32 v101, v65, v97
	v_mul_f32_e32 v62, v62, v81
	v_mul_f32_e32 v63, v63, v81
	v_mul_f32_e32 v64, v64, v81
	v_mul_f32_e32 v65, v65, v81
	v_lshlrev_b32_e32 v2, 2, v125
	v_lshlrev_b32_e32 v3, 12, v125
	v_lshl_add_u32 v3, v7, 1, v3
	ds_bpermute_b32 v106, v48, v98
	ds_bpermute_b32 v107, v48, v99
	ds_bpermute_b32 v108, v48, v100
	ds_bpermute_b32 v109, v48, v101
	s_waitcnt lgkmcnt(0)
	v_add_f32_e32 v98, v98, v106
	v_add_f32_e32 v99, v99, v107
	v_add_f32_e32 v100, v100, v108
	v_add_f32_e32 v101, v101, v109
	ds_bpermute_b32 v106, v1, v98
	ds_bpermute_b32 v107, v1, v99
	ds_bpermute_b32 v108, v1, v100
	ds_bpermute_b32 v109, v1, v101
	s_waitcnt lgkmcnt(0)
	v_add_f32_e32 v98, v98, v106
	v_add_f32_e32 v99, v99, v107
	v_add_f32_e32 v100, v100, v108
	v_add_f32_e32 v101, v101, v109
	s_mov_b64 exec, s[36:37]
	global_atomic_add_f32 v2, v98, s[78:79] offset:0
	global_atomic_add_f32 v2, v99, s[78:79] offset:4
	global_atomic_add_f32 v2, v100, s[78:79] offset:8
	global_atomic_add_f32 v2, v101, s[78:79] offset:12
	s_mov_b64 exec, -1
	v_cvt_pk_bf16_f32 v20, v204, v208
	v_cvt_pk_bf16_f32 v21, v212, v216
	v_cvt_pk_bf16_f32 v22, v220, v224
	v_cvt_pk_bf16_f32 v23, v228, v232
	global_store_dwordx4 v3, v[20:23], s[4:5]
	v_cvt_pk_bf16_f32 v24, v236, v240
	v_cvt_pk_bf16_f32 v25, v244, v248
	v_cvt_pk_bf16_f32 v26, v50, v54
	v_cvt_pk_bf16_f32 v27, v58, v62
	global_store_dwordx4 v3, v[24:27], s[4:5] offset:16
	v_lshlrev_b32_e32 v19, 16, v20
	v_and_b32_e32 v114, 0xffff0000, v20
	v_add_f32_e32 v114, v19, v114
	v_lshlrev_b32_e32 v19, 16, v21
	v_and_b32_e32 v115, 0xffff0000, v21
	v_add_f32_e32 v115, v19, v115
	v_lshlrev_b32_e32 v19, 16, v22
	v_and_b32_e32 v116, 0xffff0000, v22
	v_add_f32_e32 v116, v19, v116
	v_lshlrev_b32_e32 v19, 16, v23
	v_and_b32_e32 v117, 0xffff0000, v23
	v_add_f32_e32 v117, v19, v117
	v_lshlrev_b32_e32 v19, 16, v24
	v_and_b32_e32 v118, 0xffff0000, v24
	v_add_f32_e32 v118, v19, v118
	v_lshlrev_b32_e32 v19, 16, v25
	v_and_b32_e32 v119, 0xffff0000, v25
	v_add_f32_e32 v119, v19, v119
	v_lshlrev_b32_e32 v19, 16, v26
	v_and_b32_e32 v120, 0xffff0000, v26
	v_add_f32_e32 v120, v19, v120
	v_lshlrev_b32_e32 v19, 16, v27
	v_and_b32_e32 v121, 0xffff0000, v27
	v_add_f32_e32 v121, v19, v121
	v_add_f32_e32 v114, v114, v115
	v_add_f32_e32 v116, v116, v117
	v_add_f32_e32 v118, v118, v119
	v_add_f32_e32 v120, v120, v121
	v_add_f32_e32 v114, v114, v116
	v_add_f32_e32 v118, v118, v120
	v_add_f32_e32 v110, v114, v118
	s_add_u32 s4, s4, 0x1000
	s_addc_u32 s5, s5, 0
	v_cvt_pk_bf16_f32 v28, v205, v209
	v_cvt_pk_bf16_f32 v29, v213, v217
	v_cvt_pk_bf16_f32 v30, v221, v225
	v_cvt_pk_bf16_f32 v31, v229, v233
	global_store_dwordx4 v3, v[28:31], s[4:5]
	v_cvt_pk_bf16_f32 v32, v237, v241
	v_cvt_pk_bf16_f32 v33, v245, v249
	v_cvt_pk_bf16_f32 v34, v51, v55
	v_cvt_pk_bf16_f32 v35, v59, v63
	global_store_dwordx4 v3, v[32:35], s[4:5] offset:16
	v_lshlrev_b32_e32 v19, 16, v28
	v_and_b32_e32 v114, 0xffff0000, v28
	v_add_f32_e32 v114, v19, v114
	v_lshlrev_b32_e32 v19, 16, v29
	v_and_b32_e32 v115, 0xffff0000, v29
	v_add_f32_e32 v115, v19, v115
	v_lshlrev_b32_e32 v19, 16, v30
	v_and_b32_e32 v116, 0xffff0000, v30
	v_add_f32_e32 v116, v19, v116
	v_lshlrev_b32_e32 v19, 16, v31
	v_and_b32_e32 v117, 0xffff0000, v31
	v_add_f32_e32 v117, v19, v117
	v_lshlrev_b32_e32 v19, 16, v32
	v_and_b32_e32 v118, 0xffff0000, v32
	v_add_f32_e32 v118, v19, v118
	v_lshlrev_b32_e32 v19, 16, v33
	v_and_b32_e32 v119, 0xffff0000, v33
	v_add_f32_e32 v119, v19, v119
	v_lshlrev_b32_e32 v19, 16, v34
	v_and_b32_e32 v120, 0xffff0000, v34
	v_add_f32_e32 v120, v19, v120
	v_lshlrev_b32_e32 v19, 16, v35
	v_and_b32_e32 v121, 0xffff0000, v35
	v_add_f32_e32 v121, v19, v121
	v_add_f32_e32 v114, v114, v115
	v_add_f32_e32 v116, v116, v117
	v_add_f32_e32 v118, v118, v119
	v_add_f32_e32 v120, v120, v121
	v_add_f32_e32 v114, v114, v116
	v_add_f32_e32 v118, v118, v120
	v_add_f32_e32 v111, v114, v118
	s_add_u32 s4, s4, 0x1000
	s_addc_u32 s5, s5, 0
	v_cvt_pk_bf16_f32 v36, v206, v210
	v_cvt_pk_bf16_f32 v37, v214, v218
	v_cvt_pk_bf16_f32 v38, v222, v226
	v_cvt_pk_bf16_f32 v39, v230, v234
	global_store_dwordx4 v3, v[36:39], s[4:5]
	v_cvt_pk_bf16_f32 v40, v238, v242
	v_cvt_pk_bf16_f32 v41, v246, v250
	v_cvt_pk_bf16_f32 v42, v52, v56
	v_cvt_pk_bf16_f32 v43, v60, v64
	global_store_dwordx4 v3, v[40:43], s[4:5] offset:16
	v_lshlrev_b32_e32 v19, 16, v36
	v_and_b32_e32 v114, 0xffff0000, v36
	v_add_f32_e32 v114, v19, v114
	v_lshlrev_b32_e32 v19, 16, v37
	v_and_b32_e32 v115, 0xffff0000, v37
	v_add_f32_e32 v115, v19, v115
	v_lshlrev_b32_e32 v19, 16, v38
	v_and_b32_e32 v116, 0xffff0000, v38
	v_add_f32_e32 v116, v19, v116
	v_lshlrev_b32_e32 v19, 16, v39
	v_and_b32_e32 v117, 0xffff0000, v39
	v_add_f32_e32 v117, v19, v117
	v_lshlrev_b32_e32 v19, 16, v40
	v_and_b32_e32 v118, 0xffff0000, v40
	v_add_f32_e32 v118, v19, v118
	v_lshlrev_b32_e32 v19, 16, v41
	v_and_b32_e32 v119, 0xffff0000, v41
	v_add_f32_e32 v119, v19, v119
	v_lshlrev_b32_e32 v19, 16, v42
	v_and_b32_e32 v120, 0xffff0000, v42
	v_add_f32_e32 v120, v19, v120
	v_lshlrev_b32_e32 v19, 16, v43
	v_and_b32_e32 v121, 0xffff0000, v43
	v_add_f32_e32 v121, v19, v121
	v_add_f32_e32 v114, v114, v115
	v_add_f32_e32 v116, v116, v117
	v_add_f32_e32 v118, v118, v119
	v_add_f32_e32 v120, v120, v121
	v_add_f32_e32 v114, v114, v116
	v_add_f32_e32 v118, v118, v120
	v_add_f32_e32 v112, v114, v118
	s_add_u32 s4, s4, 0x1000
	s_addc_u32 s5, s5, 0
	v_cvt_pk_bf16_f32 v20, v207, v211
	v_cvt_pk_bf16_f32 v21, v215, v219
	v_cvt_pk_bf16_f32 v22, v223, v227
	v_cvt_pk_bf16_f32 v23, v231, v235
	global_store_dwordx4 v3, v[20:23], s[4:5]
	v_cvt_pk_bf16_f32 v24, v239, v243
	v_cvt_pk_bf16_f32 v25, v247, v251
	v_cvt_pk_bf16_f32 v26, v53, v57
	v_cvt_pk_bf16_f32 v27, v61, v65
	global_store_dwordx4 v3, v[24:27], s[4:5] offset:16
	v_lshlrev_b32_e32 v19, 16, v20
	v_and_b32_e32 v114, 0xffff0000, v20
	v_add_f32_e32 v114, v19, v114
	v_lshlrev_b32_e32 v19, 16, v21
	v_and_b32_e32 v115, 0xffff0000, v21
	v_add_f32_e32 v115, v19, v115
	v_lshlrev_b32_e32 v19, 16, v22
	v_and_b32_e32 v116, 0xffff0000, v22
	v_add_f32_e32 v116, v19, v116
	v_lshlrev_b32_e32 v19, 16, v23
	v_and_b32_e32 v117, 0xffff0000, v23
	v_add_f32_e32 v117, v19, v117
	v_lshlrev_b32_e32 v19, 16, v24
	v_and_b32_e32 v118, 0xffff0000, v24
	v_add_f32_e32 v118, v19, v118
	v_lshlrev_b32_e32 v19, 16, v25
	v_and_b32_e32 v119, 0xffff0000, v25
	v_add_f32_e32 v119, v19, v119
	v_lshlrev_b32_e32 v19, 16, v26
	v_and_b32_e32 v120, 0xffff0000, v26
	v_add_f32_e32 v120, v19, v120
	v_lshlrev_b32_e32 v19, 16, v27
	v_and_b32_e32 v121, 0xffff0000, v27
	v_add_f32_e32 v121, v19, v121
	v_add_f32_e32 v114, v114, v115
	v_add_f32_e32 v116, v116, v117
	v_add_f32_e32 v118, v118, v119
	v_add_f32_e32 v120, v120, v121
	v_add_f32_e32 v114, v114, v116
	v_add_f32_e32 v118, v118, v120
	v_add_f32_e32 v113, v114, v118
	ds_bpermute_b32 v106, v48, v110
	ds_bpermute_b32 v107, v48, v111
	ds_bpermute_b32 v108, v48, v112
	ds_bpermute_b32 v109, v48, v113
	s_waitcnt lgkmcnt(0)
	v_add_f32_e32 v110, v110, v106
	v_add_f32_e32 v111, v111, v107
	v_add_f32_e32 v112, v112, v108
	v_add_f32_e32 v113, v113, v109
	ds_bpermute_b32 v106, v1, v110
	ds_bpermute_b32 v107, v1, v111
	ds_bpermute_b32 v108, v1, v112
	ds_bpermute_b32 v109, v1, v113
	s_waitcnt lgkmcnt(0)
	v_add_f32_e32 v110, v110, v106
	v_add_f32_e32 v111, v111, v107
	v_add_f32_e32 v112, v112, v108
	v_add_f32_e32 v113, v113, v109
	s_mov_b64 exec, s[36:37]
	global_atomic_add_f32 v2, v110, s[76:77] offset:0
	global_atomic_add_f32 v2, v111, s[76:77] offset:4
	global_atomic_add_f32 v2, v112, s[76:77] offset:8
	global_atomic_add_f32 v2, v113, s[76:77] offset:12
	s_mov_b64 exec, -1
	s_waitcnt vmcnt(16)
	s_branch .Lw2tw_loop
.Lw2tw_rest:
	s_waitcnt vmcnt(0)
	v_lshlrev_b32_e32 v2, 4, v0
	v_add_u32_e32 v3, 0x10000, v2
	ds_read_b128 v[66:69], v2 offset:0
	ds_read_b128 v[70:73], v2 offset:8192
	ds_read_b128 v[74:77], v2 offset:16384
	ds_read_b128 v[78:81], v2 offset:24576
	ds_read_b128 v[82:85], v2 offset:32768
	ds_read_b128 v[86:89], v2 offset:40960
	ds_read_b128 v[90:93], v2 offset:49152
	ds_read_b128 v[94:97], v2 offset:57344
	ds_read_b128 v[98:101], v3 offset:0
	ds_read_b128 v[102:105], v3 offset:8192
	ds_read_b128 v[106:109], v3 offset:16384
	ds_read_b128 v[110:113], v3 offset:24576
	ds_read_b128 v[114:117], v3 offset:32768
	ds_read_b128 v[118:121], v3 offset:40960
	ds_read_b128 v[122:125], v3 offset:49152
	ds_read_b128 v[126:129], v3 offset:57344
	s_waitcnt lgkmcnt(0)
	s_mov_b32 s99, 1
	s_movk_i32 s98, 0x410
	s_movk_i32 s100, 0x9
	s_add_u32 s0, s86, 0xc800
	s_addc_u32 s1, s87, 0
	v_writelane_b32 v254, s0, 22
	v_mov_b32_e32 v1, v0
	s_branch .Lmix1_entry

.LBB0_1229:
	s_or_b64 exec, exec, s[0:1]
	s_waitcnt lgkmcnt(0)
	s_barrier
	ds_read_b32 v1, v155
	s_movk_i32 s0, 0x56f
	s_waitcnt lgkmcnt(0)
	v_add_u32_e32 v1, s98, v1
	v_cmp_lt_u32_e32 vcc, s0, v1
	v_readfirstlane_b32 s42, v1
	s_mov_b64 s[0:1], -1
	s_cbranch_vccnz .LBB0_1224
	s_cmpk_gt_u32 s42, 0x2ff
	s_cbranch_scc1 .Lq_nomap
	s_cmpk_lt_u32 s42, 0xc0
	s_cbranch_scc1 .Lq_nomap
	s_cmpk_lt_u32 s42, 0x2c0
	s_cbranch_scc1 .Lq_g1
	s_sub_u32 s42, s42, 0x200
	s_branch .Lq_nomap
